# strategy #8 (MFMA<->VALU interleave): v42 + SB tile: PV MFMAs of key steps 0 and 2 (8 of 16) issued early, spread through the softmax VALU of blocks 691-698 with their own V^T reads; tail keeps key st
# baseline (speedup 1.0000x reference)
.LBB0_691:
	v_cvt_pk_bf16_f32 v224, v45, v204
	v_cvt_pk_bf16_f32 v225, v42, v43
	v_cvt_pk_bf16_f32 v226, v98, v99
	v_cvt_pk_bf16_f32 v227, v86, v87
	v_cvt_pk_bf16_f32 v228, v34, v44
	v_cvt_pk_bf16_f32 v229, v40, v41
	v_cvt_pk_bf16_f32 v230, v46, v47
	v_cvt_pk_bf16_f32 v231, v48, v49
	v_add_u32_e32 v232, s53, v200
	ds_read_b64_tr_b16 v[236:237], v232 offset:0
	ds_read_b64_tr_b16 v[238:239], v232 offset:2048
	ds_read_b64_tr_b16 v[240:241], v232 offset:512
	ds_read_b64_tr_b16 v[242:243], v232 offset:2560
	ds_read_b64_tr_b16 v[244:245], v232 offset:1024
	ds_read_b64_tr_b16 v[246:247], v232 offset:3072
	ds_read_b64_tr_b16 v[248:249], v232 offset:1536
	ds_read_b64_tr_b16 v[250:251], v232 offset:3584
	v_permlane32_swap_b32_e32 v224, v226
	v_permlane32_swap_b32_e32 v225, v227
	v_permlane32_swap_b32_e32 v228, v230
	v_permlane32_swap_b32_e32 v229, v231
	v_cndmask_b32_e64 v36, v207, v208, s[38:39]
	v_cndmask_b32_e64 v38, v209, v210, s[38:39]
	v_sub_f32_e32 v37, v36, v179
	v_sub_f32_e32 v39, v38, v177
	s_waitcnt lgkmcnt(6)
	v_mfma_f32_32x32x16_bf16 v[66:81], v[224:227], v[236:239], v[66:81]
	ds_read_b64_tr_b16 v[236:237], v232 offset:8192
	ds_read_b64_tr_b16 v[238:239], v232 offset:10240
	v_sub_f32_e32 v36, v37, v178
	v_sub_f32_e32 v38, v39, v176
	v_sub_f32_e32 v85, v36, v107
	v_sub_f32_e32 v101, v38, v105
	v_sub_f32_e32 v84, v85, v106
	v_sub_f32_e32 v100, v101, v104
	s_waitcnt lgkmcnt(6)
	v_mfma_f32_32x32x16_bf16 v[50:65], v[224:227], v[240:243], v[50:65]
	ds_read_b64_tr_b16 v[240:241], v232 offset:8704
	ds_read_b64_tr_b16 v[242:243], v232 offset:10752
	v_pk_add_f32 v[88:89], v[88:89], v[100:101]
	v_pk_add_f32 v[84:85], v[90:91], v[84:85]
	v_exp_f32_e32 v90, v88
	v_exp_f32_e32 v91, v89
	s_waitcnt lgkmcnt(6)
	v_mfma_f32_32x32x16_bf16 v[18:33], v[224:227], v[244:247], v[18:33]
	ds_read_b64_tr_b16 v[244:245], v232 offset:9216
	ds_read_b64_tr_b16 v[246:247], v232 offset:11264
	v_exp_f32_e32 v84, v84
	v_exp_f32_e32 v85, v85
	s_and_b64 vcc, exec, s[42:43]
	s_cbranch_vccz .Lsbd_692
.LBB0_693:
	s_waitcnt lgkmcnt(6)
	v_mfma_f32_32x32x16_bf16 v[2:17], v[224:227], v[248:251], v[2:17]
	ds_read_b64_tr_b16 v[248:249], v232 offset:9728
	ds_read_b64_tr_b16 v[250:251], v232 offset:11776
	v_pk_add_f32 v[38:39], v[92:93], v[38:39]
	v_pk_add_f32 v[36:37], v[102:103], v[36:37]
	v_exp_f32_e32 v92, v38
	v_exp_f32_e32 v93, v39
	s_waitcnt lgkmcnt(6)
	v_mfma_f32_32x32x16_bf16 v[66:81], v[228:231], v[236:239], v[66:81]
	v_exp_f32_e32 v88, v36
	v_exp_f32_e32 v89, v37
	s_and_b64 vcc, exec, s[42:43]
	s_cbranch_vccz .Lsbd_694
.LBB0_695:
	v_cndmask_b32_e64 v36, v202, v203, s[38:39]
	v_cndmask_b32_e64 v38, v205, v206, s[38:39]
	v_sub_f32_e32 v37, v36, v185
	s_waitcnt lgkmcnt(4)
	v_mfma_f32_32x32x16_bf16 v[50:65], v[228:231], v[240:243], v[50:65]
	v_sub_f32_e32 v39, v38, v113
	v_sub_f32_e32 v36, v37, v184
	v_sub_f32_e32 v38, v39, v112
	v_sub_f32_e32 v101, v36, v175
	v_sub_f32_e32 v103, v38, v173
	v_sub_f32_e32 v100, v101, v174
	v_sub_f32_e32 v102, v103, v172
	v_pk_add_f32 v[94:95], v[94:95], v[102:103]
	v_pk_add_f32 v[102:103], v[108:109], v[100:101]
	s_waitcnt lgkmcnt(2)
	v_mfma_f32_32x32x16_bf16 v[18:33], v[228:231], v[244:247], v[18:33]
	v_exp_f32_e32 v100, v94
	v_exp_f32_e32 v101, v95
	v_exp_f32_e32 v94, v102
	v_exp_f32_e32 v95, v103
	s_and_b64 vcc, exec, s[42:43]
	s_cbranch_vccz .Lsbd_696
.LBB0_697:
	v_pk_add_f32 v[38:39], v[96:97], v[38:39]
	v_pk_add_f32 v[36:37], v[110:111], v[36:37]
	s_waitcnt lgkmcnt(0)
	v_mfma_f32_32x32x16_bf16 v[2:17], v[228:231], v[248:251], v[2:17]
	v_exp_f32_e32 v102, v38
	v_exp_f32_e32 v103, v39
	v_exp_f32_e32 v96, v36
	v_exp_f32_e32 v97, v37
	s_and_b64 vcc, exec, s[42:43]
	s_cbranch_vccz .Lsbd_698
.LBB0_699:
	v_add_f32_e32 v202, v83, v82
	v_cvt_pk_bf16_f32 v90, v90, v91
	v_cvt_pk_bf16_f32 v91, v92, v93
	v_cvt_pk_bf16_f32 v92, v100, v101
	v_cvt_pk_bf16_f32 v93, v102, v103
	v_cvt_pk_bf16_f32 v46, v84, v85
	v_cvt_pk_bf16_f32 v47, v88, v89
	v_cvt_pk_bf16_f32 v48, v94, v95
	v_cvt_pk_bf16_f32 v49, v96, v97
	ds_read_b64_tr_b16 v[86:87], v232 offset:4096
	ds_read_b64_tr_b16 v[88:89], v232 offset:6144
	ds_read_b64_tr_b16 v[98:99], v232 offset:12288
	ds_read_b64_tr_b16 v[100:101], v232 offset:14336
	ds_read_b64_tr_b16 v[82:83], v232 offset:4608
	ds_read_b64_tr_b16 v[84:85], v232 offset:6656
	ds_read_b64_tr_b16 v[94:95], v232 offset:12800
	ds_read_b64_tr_b16 v[96:97], v232 offset:14848
	v_permlane32_swap_b32_e32 v90, v92
	v_permlane32_swap_b32_e32 v91, v93
	v_permlane32_swap_b32_e32 v46, v48
	v_permlane32_swap_b32_e32 v47, v49
	s_waitcnt lgkmcnt(4)
	v_mfma_f32_32x32x16_bf16 v[66:81], v[90:93], v[86:89], v[66:81]
	v_mfma_f32_32x32x16_bf16 v[66:81], v[46:49], v[98:101], v[66:81]
	ds_read_b64_tr_b16 v[86:87], v232 offset:5120
	ds_read_b64_tr_b16 v[88:89], v232 offset:7168
	ds_read_b64_tr_b16 v[98:99], v232 offset:13312
	ds_read_b64_tr_b16 v[100:101], v232 offset:15360
	s_waitcnt lgkmcnt(4)
	v_mfma_f32_32x32x16_bf16 v[50:65], v[90:93], v[82:85], v[50:65]
	v_mfma_f32_32x32x16_bf16 v[50:65], v[46:49], v[94:97], v[50:65]
	ds_read_b64_tr_b16 v[82:83], v232 offset:5632
	ds_read_b64_tr_b16 v[84:85], v232 offset:7680
	ds_read_b64_tr_b16 v[94:95], v232 offset:13824
	ds_read_b64_tr_b16 v[96:97], v232 offset:15872
	s_waitcnt lgkmcnt(4)
	v_mfma_f32_32x32x16_bf16 v[18:33], v[90:93], v[86:89], v[18:33]
	v_mfma_f32_32x32x16_bf16 v[18:33], v[46:49], v[98:101], v[18:33]
	s_mov_b32 s4, 0xc31eb24b
	v_cmp_gt_f32_e32 vcc, s4, v202
	s_cmp_eq_u64 vcc, exec
	s_cselect_b64 s[4:5], -1, 0
	s_waitcnt lgkmcnt(0)
	v_mfma_f32_32x32x16_bf16 v[2:17], v[90:93], v[82:85], v[2:17]
	v_mfma_f32_32x32x16_bf16 v[2:17], v[46:49], v[94:97], v[2:17]
	s_and_saveexec_b64 s[42:43], s[40:41]
	s_cbranch_execz .LBB0_662
